# P0 cache_k/cache_v conversion loops unrolled x4 (four loads in flight per trip)
# speedup vs baseline: 1.2265x; 1.0024x over previous
.LBB0_138:
	v_mul_hi_u32 v1, v12, s33
	v_lshrrev_b32_e32 v1, 18, v1
	v_mul_u32_u24_e32 v3, 0x60000, v1
	v_sub_u32_e32 v3, v12, v3
	v_mad_u64_u32 v[14:15], s[0:1], v1, s35, v[8:9]
	v_lshlrev_b32_e32 v4, 2, v3
	v_lshl_add_u64 v[14:15], v[4:5], 2, v[14:15]
	global_load_dwordx4 v[20:23], v[14:15], off
	v_mad_u64_u32 v[36:37], s[0:1], v1, s38, v[10:11]
	v_lshlrev_b32_e32 v4, 3, v3
	v_lshl_add_u64 v[36:37], v[36:37], 0, v[4:5]
	v_lshl_add_u64 v[12:13], v[12:13], 0, s[6:7]
	v_mul_hi_u32 v1, v12, s33
	v_lshrrev_b32_e32 v1, 18, v1
	v_mul_u32_u24_e32 v3, 0x60000, v1
	v_sub_u32_e32 v3, v12, v3
	v_mad_u64_u32 v[14:15], s[0:1], v1, s35, v[8:9]
	v_lshlrev_b32_e32 v4, 2, v3
	v_lshl_add_u64 v[14:15], v[4:5], 2, v[14:15]
	global_load_dwordx4 v[24:27], v[14:15], off
	v_mad_u64_u32 v[38:39], s[0:1], v1, s38, v[10:11]
	v_lshlrev_b32_e32 v4, 3, v3
	v_lshl_add_u64 v[38:39], v[38:39], 0, v[4:5]
	v_lshl_add_u64 v[12:13], v[12:13], 0, s[6:7]
	v_mul_hi_u32 v1, v12, s33
	v_lshrrev_b32_e32 v1, 18, v1
	v_mul_u32_u24_e32 v3, 0x60000, v1
	v_sub_u32_e32 v3, v12, v3
	v_mad_u64_u32 v[14:15], s[0:1], v1, s35, v[8:9]
	v_lshlrev_b32_e32 v4, 2, v3
	v_lshl_add_u64 v[14:15], v[4:5], 2, v[14:15]
	global_load_dwordx4 v[28:31], v[14:15], off
	v_mad_u64_u32 v[40:41], s[0:1], v1, s38, v[10:11]
	v_lshlrev_b32_e32 v4, 3, v3
	v_lshl_add_u64 v[40:41], v[40:41], 0, v[4:5]
	v_lshl_add_u64 v[12:13], v[12:13], 0, s[6:7]
	v_mul_hi_u32 v1, v12, s33
	v_lshrrev_b32_e32 v1, 18, v1
	v_mul_u32_u24_e32 v3, 0x60000, v1
	v_sub_u32_e32 v3, v12, v3
	v_mad_u64_u32 v[14:15], s[0:1], v1, s35, v[8:9]
	v_lshlrev_b32_e32 v4, 2, v3
	v_lshl_add_u64 v[14:15], v[4:5], 2, v[14:15]
	global_load_dwordx4 v[32:35], v[14:15], off
	v_mad_u64_u32 v[42:43], s[0:1], v1, s38, v[10:11]
	v_lshlrev_b32_e32 v4, 3, v3
	v_lshl_add_u64 v[42:43], v[42:43], 0, v[4:5]
	v_lshl_add_u64 v[12:13], v[12:13], 0, s[6:7]
	v_cmp_lt_u64_e64 s[0:1], s[20:21], v[12:13]
	s_or_b64 s[10:11], s[0:1], s[10:11]
	s_waitcnt vmcnt(3)
	v_cvt_pk_bf16_f32 v20, v20, v21
	v_cvt_pk_bf16_f32 v21, v22, v23
	global_store_dwordx2 v[36:37], v[20:21], off
	s_waitcnt vmcnt(3)
	v_cvt_pk_bf16_f32 v24, v24, v25
	v_cvt_pk_bf16_f32 v25, v26, v27
	global_store_dwordx2 v[38:39], v[24:25], off
	s_waitcnt vmcnt(3)
	v_cvt_pk_bf16_f32 v28, v28, v29
	v_cvt_pk_bf16_f32 v29, v30, v31
	global_store_dwordx2 v[40:41], v[28:29], off
	s_waitcnt vmcnt(3)
	v_cvt_pk_bf16_f32 v32, v32, v33
	v_cvt_pk_bf16_f32 v33, v34, v35
	global_store_dwordx2 v[42:43], v[32:33], off
	s_andn2_b64 exec, exec, s[10:11]
	s_cbranch_execnz .LBB0_138

.LBB0_141:
	v_mul_hi_u32 v1, v12, s33
	v_lshrrev_b32_e32 v1, 18, v1
	v_mul_u32_u24_e32 v3, 0x60000, v1
	v_sub_u32_e32 v3, v12, v3
	v_mad_u64_u32 v[14:15], s[38:39], v1, s35, v[8:9]
	v_lshlrev_b32_e32 v4, 2, v3
	v_lshl_add_u64 v[14:15], v[4:5], 2, v[14:15]
	global_load_dwordx4 v[20:23], v[14:15], off
	v_mad_u64_u32 v[36:37], s[38:39], v1, s22, v[10:11]
	v_lshlrev_b32_e32 v4, 3, v3
	v_lshl_add_u64 v[36:37], v[36:37], 0, v[4:5]
	v_lshl_add_u64 v[12:13], v[12:13], 0, s[4:5]
	v_mul_hi_u32 v1, v12, s33
	v_lshrrev_b32_e32 v1, 18, v1
	v_mul_u32_u24_e32 v3, 0x60000, v1
	v_sub_u32_e32 v3, v12, v3
	v_mad_u64_u32 v[14:15], s[38:39], v1, s35, v[8:9]
	v_lshlrev_b32_e32 v4, 2, v3
	v_lshl_add_u64 v[14:15], v[4:5], 2, v[14:15]
	global_load_dwordx4 v[24:27], v[14:15], off
	v_mad_u64_u32 v[38:39], s[38:39], v1, s22, v[10:11]
	v_lshlrev_b32_e32 v4, 3, v3
	v_lshl_add_u64 v[38:39], v[38:39], 0, v[4:5]
	v_lshl_add_u64 v[12:13], v[12:13], 0, s[4:5]
	v_mul_hi_u32 v1, v12, s33
	v_lshrrev_b32_e32 v1, 18, v1
	v_mul_u32_u24_e32 v3, 0x60000, v1
	v_sub_u32_e32 v3, v12, v3
	v_mad_u64_u32 v[14:15], s[38:39], v1, s35, v[8:9]
	v_lshlrev_b32_e32 v4, 2, v3
	v_lshl_add_u64 v[14:15], v[4:5], 2, v[14:15]
	global_load_dwordx4 v[28:31], v[14:15], off
	v_mad_u64_u32 v[40:41], s[38:39], v1, s22, v[10:11]
	v_lshlrev_b32_e32 v4, 3, v3
	v_lshl_add_u64 v[40:41], v[40:41], 0, v[4:5]
	v_lshl_add_u64 v[12:13], v[12:13], 0, s[4:5]
	v_mul_hi_u32 v1, v12, s33
	v_lshrrev_b32_e32 v1, 18, v1
	v_mul_u32_u24_e32 v3, 0x60000, v1
	v_sub_u32_e32 v3, v12, v3
	v_mad_u64_u32 v[14:15], s[38:39], v1, s35, v[8:9]
	v_lshlrev_b32_e32 v4, 2, v3
	v_lshl_add_u64 v[14:15], v[4:5], 2, v[14:15]
	global_load_dwordx4 v[32:35], v[14:15], off
	v_mad_u64_u32 v[42:43], s[38:39], v1, s22, v[10:11]
	v_lshlrev_b32_e32 v4, 3, v3
	v_lshl_add_u64 v[42:43], v[42:43], 0, v[4:5]
	v_lshl_add_u64 v[12:13], v[12:13], 0, s[4:5]
	v_cmp_lt_u64_e32 vcc, s[10:11], v[12:13]
	s_or_b64 s[6:7], vcc, s[6:7]
	s_waitcnt vmcnt(3)
	v_cvt_pk_bf16_f32 v20, v20, v21
	v_cvt_pk_bf16_f32 v21, v22, v23
	global_store_dwordx2 v[36:37], v[20:21], off
	s_waitcnt vmcnt(3)
	v_cvt_pk_bf16_f32 v24, v24, v25
	v_cvt_pk_bf16_f32 v25, v26, v27
	global_store_dwordx2 v[38:39], v[24:25], off
	s_waitcnt vmcnt(3)
	v_cvt_pk_bf16_f32 v28, v28, v29
	v_cvt_pk_bf16_f32 v29, v30, v31
	global_store_dwordx2 v[40:41], v[28:29], off
	s_waitcnt vmcnt(3)
	v_cvt_pk_bf16_f32 v32, v32, v33
	v_cvt_pk_bf16_f32 v33, v34, v35
	global_store_dwordx2 v[42:43], v[32:33], off
	s_andn2_b64 exec, exec, s[6:7]
	s_cbranch_execnz .LBB0_141
